# v19 + one static s_setprio 1 for waves 0-3 at the entry of every GEMM phase
# speedup vs baseline: 1.0083x; 1.0083x over previous
.LBB0_275:
	s_cmp_lt_i32 s84, 4
	s_cselect_b64 s[4:5], -1, 0
	s_cmp_gt_i32 s85, 3
	s_cselect_b64 s[6:7], -1, 0
	s_and_b64 s[4:5], s[4:5], s[6:7]
	s_andn2_b64 vcc, exec, s[4:5]
	s_cbranch_vccnz .LBB0_346
	v_readfirstlane_b32 s98, v0
	s_nop 3
	s_bitcmp1_b32 s98, 8
	s_cbranch_scc1 .Lsprio_skip_4
	s_setprio 1

.LBB0_346:
	s_cmp_lt_i32 s84, 5
	s_cselect_b64 s[4:5], -1, 0
	s_cmp_gt_i32 s85, 4
	s_cselect_b64 s[6:7], -1, 0
	s_and_b64 s[4:5], s[4:5], s[6:7]
	s_andn2_b64 vcc, exec, s[4:5]
	s_cbranch_vccnz .LBB0_453
	v_readfirstlane_b32 s98, v0
	s_nop 3
	s_bitcmp1_b32 s98, 8
	s_cbranch_scc1 .Lsprio_skip_5
	s_setprio 1

.LBB0_453:
	s_cmp_lt_i32 s84, 7
	s_cselect_b64 s[4:5], -1, 0
	s_cmp_gt_i32 s85, 6
	s_cselect_b64 s[6:7], -1, 0
	s_and_b64 s[4:5], s[4:5], s[6:7]
	s_andn2_b64 vcc, exec, s[4:5]
	s_cbranch_vccnz .LBB0_562
	v_readfirstlane_b32 s98, v0
	s_nop 3
	s_bitcmp1_b32 s98, 8
	s_cbranch_scc1 .Lsprio_skip_7
	s_setprio 1

.LBB0_691:
	s_cmp_lt_i32 s84, 10
	s_cselect_b64 s[4:5], -1, 0
	s_cmp_gt_i32 s85, 9
	s_cselect_b64 s[6:7], -1, 0
	s_and_b64 s[4:5], s[4:5], s[6:7]
	s_andn2_b64 vcc, exec, s[4:5]
	s_cbranch_vccnz .LBB0_796
	v_readfirstlane_b32 s98, v0
	s_nop 3
	s_bitcmp1_b32 s98, 8
	s_cbranch_scc1 .Lsprio_skip_10
	s_setprio 1

.LBB0_796:
	s_cmp_lt_i32 s84, 12
	s_cselect_b64 s[4:5], -1, 0
	s_cmp_gt_i32 s85, 11
	s_cselect_b64 s[6:7], -1, 0
	s_and_b64 s[4:5], s[4:5], s[6:7]
	s_andn2_b64 vcc, exec, s[4:5]
	s_cbranch_vccnz .LBB0_867
	v_readfirstlane_b32 s98, v0
	s_nop 3
	s_bitcmp1_b32 s98, 8
	s_cbranch_scc1 .Lsprio_skip_12
	s_setprio 1

.LBB0_867:
	s_cmp_lt_i32 s84, 13
	s_cselect_b64 s[4:5], -1, 0
	s_cmp_gt_i32 s85, 12
	s_cselect_b64 s[6:7], -1, 0
	s_and_b64 s[4:5], s[4:5], s[6:7]
	s_andn2_b64 vcc, exec, s[4:5]
	s_cbranch_vccnz .LBB0_974
	v_readfirstlane_b32 s98, v0
	s_nop 3
	s_bitcmp1_b32 s98, 8
	s_cbranch_scc1 .Lsprio_skip_13
	s_setprio 1

.LBB0_974:
	s_cmp_lt_i32 s84, 15
	s_cselect_b64 s[4:5], -1, 0
	s_cmp_gt_i32 s85, 14
	s_cselect_b64 s[6:7], -1, 0
	s_and_b64 s[4:5], s[4:5], s[6:7]
	s_andn2_b64 vcc, exec, s[4:5]
	s_cbranch_vccnz .LBB0_1015
	v_readfirstlane_b32 s98, v0
	s_nop 3
	s_bitcmp1_b32 s98, 8
	s_cbranch_scc1 .Lsprio_skip_15
	s_setprio 1

.LBB0_1015:
	s_cmp_lt_i32 s84, 16
	s_cselect_b64 s[4:5], -1, 0
	s_cmp_gt_i32 s85, 15
	s_cselect_b64 s[6:7], -1, 0
	s_and_b64 s[4:5], s[4:5], s[6:7]
	s_andn2_b64 vcc, exec, s[4:5]
	s_cbranch_vccnz .LBB0_1086
	v_readfirstlane_b32 s98, v0
	s_nop 3
	s_bitcmp1_b32 s98, 8
	s_cbranch_scc1 .Lsprio_skip_16
	s_setprio 1

.LBB0_1086:
	s_cmp_lt_i32 s84, 17
	s_cselect_b64 s[4:5], -1, 0
	s_cmp_gt_i32 s85, 16
	s_cselect_b64 s[6:7], -1, 0
	s_and_b64 s[4:5], s[4:5], s[6:7]
	s_andn2_b64 vcc, exec, s[4:5]
	s_cbranch_vccnz .LBB0_1193
	v_readfirstlane_b32 s98, v0
	s_nop 3
	s_bitcmp1_b32 s98, 8
	s_cbranch_scc1 .Lsprio_skip_17
	s_setprio 1

.LBB0_1193:
	s_cmp_lt_i32 s84, 19
	s_cselect_b64 s[4:5], -1, 0
	s_cmp_gt_i32 s85, 18
	s_cselect_b64 s[6:7], -1, 0
	s_and_b64 s[4:5], s[4:5], s[6:7]
	s_andn2_b64 vcc, exec, s[4:5]
	s_cbranch_vccnz .LBB0_1326
	v_readfirstlane_b32 s98, v0
	s_nop 3
	s_bitcmp1_b32 s98, 8
	s_cbranch_scc1 .Lsprio_skip_19
	s_setprio 1

.LBB0_1326:
	s_cmp_lt_i32 s84, 20
	s_cselect_b64 s[4:5], -1, 0
	s_cmp_gt_i32 s85, 19
	s_cselect_b64 s[6:7], -1, 0
	s_and_b64 s[4:5], s[4:5], s[6:7]
	s_andn2_b64 vcc, exec, s[4:5]
	s_cbranch_vccnz .LBB0_1401
	v_readfirstlane_b32 s98, v0
	s_nop 3
	s_bitcmp1_b32 s98, 8
	s_cbranch_scc1 .Lsprio_skip_20
	s_setprio 1

.LBB0_1489:
	s_cmp_lt_i32 s84, 22
	s_cselect_b64 s[4:5], -1, 0
	s_cmp_gt_i32 s85, 21
	s_cselect_b64 s[6:7], -1, 0
	s_and_b64 s[4:5], s[4:5], s[6:7]
	s_andn2_b64 vcc, exec, s[4:5]
	s_cbranch_vccnz .LBB0_1594
	v_readfirstlane_b32 s98, v0
	s_nop 3
	s_bitcmp1_b32 s98, 8
	s_cbranch_scc1 .Lsprio_skip_22
	s_setprio 1

.LBB0_1594:
	s_cmp_lt_i32 s84, 24
	s_cselect_b64 s[4:5], -1, 0
	s_cmp_gt_i32 s85, 23
	s_cselect_b64 s[6:7], -1, 0
	s_and_b64 s[4:5], s[4:5], s[6:7]
	s_andn2_b64 vcc, exec, s[4:5]
	s_cbranch_vccnz .LBB0_1665
	v_readfirstlane_b32 s98, v0
	s_nop 3
	s_bitcmp1_b32 s98, 8
	s_cbranch_scc1 .Lsprio_skip_24
	s_setprio 1

.LBB0_1665:
	s_cmp_lt_i32 s84, 25
	s_cselect_b64 s[4:5], -1, 0
	s_cmp_gt_i32 s85, 24
	s_cselect_b64 s[6:7], -1, 0
	s_and_b64 s[4:5], s[4:5], s[6:7]
	s_andn2_b64 vcc, exec, s[4:5]
	s_cbranch_vccnz .LBB0_1718
	v_readfirstlane_b32 s98, v0
	s_nop 3
	s_bitcmp1_b32 s98, 8
	s_cbranch_scc1 .Lsprio_skip_25
	s_setprio 1
